# v56 + P7 ssp tile prefetched to spare LDS by LDS-DMA (static LDS +16KB), epilogue reads via ds_read
# speedup vs baseline: 1.0032x; 1.0032x over previous
; #define PG8_STAGE(bufoff, gbase, voff) do { _Pragma("unroll") for (int _i = 0; _i < 2; ++_i) \
;         __builtin_amdgcn_global_load_lds((const unsigned*)((const char*)(gbase) + (voff)[_i]), (LAS unsigned*)(lds + (bufoff) + ldsw + _i * 8192), 16, 0, 0); } while (0)
; #define PG8_WAIT_V(n) asm volatile("s_waitcnt vmcnt(" #n ")" ::: "memory")
; #define PG8_BAR __builtin_amdgcn_s_barrier()
; template <class Epi>
; __device__ __forceinline__ void gemm_phase(LAS unsigned char* lds, const Gemm g, const StaticOrder& S, const Epi& E) {
;     ...
;         voffA[i] = (unsigned)(R * lda + C) * 2u; voffB[i] = (unsigned)(Rb * K + C) * 2u; }
;     const size_t kstep = (size_t)(BK * 2);
;     const size_t hstepA = (size_t)HALF * lda * 2, hstepB = (size_t)HALF * K * 2;
;     const size_t tstepA = 2 * hstepA, tstepB = 2 * hstepB;
;     const unsigned ldsw = (unsigned)wid * 1024u;
;     const int aoff = lds_byte(wr * 64 + fr, fq * 8), boff = lds_byte(wc * 32 + fr, fq * 8);
;     ...
;     Unit cur, nxt; int ui = 0;
;     if (!S.next(0, cur)) return;
;     f32x4 acc[2][2][4][2];
; #pragma unroll
;     for (int a = 0; a < 2; ++a)
; #pragma unroll
;         for (int b = 0; b < 2; ++b)
; #pragma unroll
;             for (int m = 0; m < 4; ++m)
; #pragma unroll
;                 for (int n = 0; n < 2; ++n) acc[a][b][m][n] = (f32x4){0.f, 0.f, 0.f, 0.f};
;     bf16x8 At[4][2], B0[2][2], B1[2][2];
;     const size_t aslab = g.aslab ? g.aslab : 32 * tstepA;
;     const char* cA = (const char*)g.A + (size_t)(cur.pm >> 5) * aslab + (size_t)(cur.pm & 31) * tstepA; const char* cB = (const char*)g.Bt + (size_t)cur.pn * tstepB;
;     PG8_STAGE(PG8_SB(0, 0), cB, voffB); PG8_STAGE(PG8_SB(0, 1), cB + hstepB, voffB); PG8_STAGE(PG8_SA(0, 0), cA, voffA); PG8_STAGE(PG8_SA(0, 1), cA + hstepA, voffA);
;     if (wr == 1) PG8_BAR;
;     PG8_WAIT_V(2); PG8_BAR;
;     PG8_STAGE(PG8_SB(1, 0), cB + kstep, voffB); PG8_STAGE(PG8_SA(1, 0), cA + kstep, voffA); PG8_STAGE(PG8_SB(1, 1), cB + hstepB + kstep, voffB);
;     PG8_WAIT_V(6); PG8_BAR;
.LBB0_923:
	s_lshl_b32 s6, s6, 5
	s_lshl_b32 s29, s7, 6
	s_lshl_b32 s13, s7, 13
	s_and_b32 s14, s6, 0x60
	s_mov_b64 s[6:7], 0x80
	s_add_i32 m0, s22, 0x18000
	v_lshl_add_u64 v[6:7], v[6:7], 0, s[6:7]
	s_lshl_b32 s15, s14, 7
	s_waitcnt vmcnt(2)
	s_barrier
	global_load_lds_dwordx4 v[6:7], off
	v_lshl_add_u64 v[2:3], v[2:3], 0, s[6:7]
	s_add_i32 m0, s22, 0x1a000
	s_add_i32 s30, s22, 0x8000
	s_add_i32 s31, s22, 0xa000
	global_load_lds_dwordx4 v[2:3], off
	v_lshl_add_u64 v[0:1], v[0:1], 0, s[6:7]
	s_mov_b32 m0, s30
	s_add_u32 s8, s2, 0x40080
	global_load_lds_dwordx4 v[0:1], off
	v_lshl_add_u64 v[0:1], v[4:5], 0, s[6:7]
	s_mov_b32 m0, s31
	s_addc_u32 s9, s3, 0
	global_load_lds_dwordx4 v[0:1], off
	s_add_i32 m0, s22, 0x1c000
	v_lshl_add_u64 v[0:1], s[8:9], 0, v[132:133]
	global_load_lds_dwordx4 v[0:1], off
	v_lshl_add_u64 v[0:1], s[8:9], 0, v[128:129]
	s_add_i32 m0, s22, 0x1e000
	v_and_b32_e32 v150, 15, v10
	global_load_lds_dwordx4 v[0:1], off
	v_bfe_u32 v0, v10, 4, 2
	v_lshlrev_b32_e32 v136, 4, v0
	v_lshlrev_b32_e32 v2, 2, v10
	v_lshl_or_b32 v152, v0, 3, s14
	v_lshlrev_b32_e32 v0, 14, v13
	v_lshl_or_b32 v1, v150, 6, v136
	v_and_b32_e32 v2, 32, v2
	v_and_b32_e32 v0, 0xffff8000, v0
	v_bitop3_b32 v3, v1, s13, v2 bitop3:0xde
	v_bitop3_b32 v151, v1, s15, v2 bitop3:0xde
	v_lshl_add_u32 v0, v12, 11, v0
	v_and_b32_e32 v1, 1, v13
	v_lshl_or_b32 v0, v1, 6, v0
	v_lshl_add_u32 v140, v14, 1, v0
	v_lshlrev_b32_e32 v0, 14, v8
	s_cmpk_lt_u32 s5, 0x100
	v_and_b32_e32 v0, 0xffff8000, v0
	s_sext_i32_i16 s42, s4
	s_cselect_b64 s[8:9], -1, 0
	s_ashr_i32 s33, s74, 31
	v_readlane_b32 s4, v235, 0
	v_lshl_add_u32 v0, v9, 11, v0
	v_and_b32_e32 v1, 1, v8
	s_waitcnt vmcnt(6)
	s_sub_u32 s4, 0x1600, s4
	v_lshl_or_b32 v0, v1, 6, v0
	s_subb_u32 s5, 0, s12
	v_lshl_add_u32 v142, v11, 1, v0
	s_add_i32 s35, 0, 0x10000
	s_add_i32 s36, 0, 0x14000
	v_mbcnt_lo_u32_b32 v0, -1, 0
	v_lshl_add_u64 v[138:139], s[10:11], 0, v[136:137]
	s_mov_b64 s[56:57], s[10:11]
	s_lshl_b32 s61, s22, 1
	s_add_i32 s61, s61, 0x24000
	s_mov_b32 s34, s74
	v_mov_b32_e32 v141, v137
	v_mov_b32_e32 v143, v137
	v_mov_b64_e32 v[144:145], s[4:5]
	v_add_u32_e32 v153, s35, v151
	v_add_u32_e32 v154, s36, v151
	v_add_u32_e32 v155, 0, v3
	v_mbcnt_hi_u32_b32 v156, -1, v0
	v_lshlrev_b32_e32 v238, 4, v156
	v_mov_b32_e32 v157, 0x358637bd
	s_mov_b32 s37, 0x4400000
	s_mov_b32 s38, 0x2d000
	s_mov_b32 s39, 0x43000
	v_mov_b32_e32 v158, 0x1fcf
	s_barrier
	s_branch .LBB0_926

; #define PG8_STAGE(bufoff, gbase, voff) do { _Pragma("unroll") for (int _i = 0; _i < 2; ++_i) \
;         __builtin_amdgcn_global_load_lds((const unsigned*)((const char*)(gbase) + (voff)[_i]), (LAS unsigned*)(lds + (bufoff) + ldsw + _i * 8192), 16, 0, 0); } while (0)
; #define PG8_LDA(dst, b, h) do { _Pragma("unroll") for (int m = 0; m < 4; ++m) _Pragma("unroll") for (int k = 0; k < 2; ++k) dst[m][k] = *(const LAS bf16x8*)(lds + PG8_SA(b, h) + aoff + m * 2048 + k * 1024); } while (0)
; #define PG8_LDB(dst, b, h) do { _Pragma("unroll") for (int n = 0; n < 2; ++n) _Pragma("unroll") for (int k = 0; k < 2; ++k) dst[n][k] = *(const LAS bf16x8*)(lds + PG8_SB(b, h) + boff + n * 2048 + k * 1024); } while (0)
; #define PG8_WAIT_V(n) asm volatile("s_waitcnt vmcnt(" #n ")" ::: "memory")
; template <int NP> __device__ __forceinline__ void load_rs(const float* ssp, int row0, int fq, float (&rs)[2][4]) {
;     ...
;         for (int ai = 0; ai < 2; ++ai)
; #pragma unroll
;             for (int m = 0; m < 4; ++m) p[ai][m] = *(const f32x4*)(ssp + (size_t)(row0 + ai * HALF + m * 16) * 16 + 4 * fq);
; template <class Epi>
; __device__ __forceinline__ void gemm_phase(LAS unsigned char* lds, const Gemm g, const StaticOrder& S, const Epi& E) {
;     ...
;         const bool has_next = S.next(ui + 1, nxt);
;         const char* nA = has_next ? (const char*)g.A + (size_t)(nxt.pm >> 5) * aslab + (size_t)(nxt.pm & 31) * tstepA : cA; const char* nB = has_next ? (const char*)g.Bt + (size_t)nxt.pn * tstepB : cB;
;         for (int t = 0; t < nt; t += 2) {
;             const bool last = (t == nt - 2);
;             const char* a1 = cA + (size_t)(t + 1) * kstep;
;             const char* a2 = last ? nA : cA + (size_t)(t + 2) * kstep; const char* b2 = last ? nB : cB + (size_t)(t + 2) * kstep;
;             const char* a3 = a2 + kstep; const char* b3 = b2 + kstep;
;             PG8_LDB(B0, 0, 0); PG8_LDB(B1, 0, 1); PG8_SCHED; PG8_LDA(At, 0, 0); PG8_STAGE(PG8_SA(1, 1), a1 + hstepA, voffA);
;             PG8_WAIT_V(8); PG8_WAIT_L(0); PG8_BAR; PG8_MMA(0, 0, At, B0); PG8_MMA(0, 1, At, B1); PG8_BAR; PG8_SCHED;
;             PG8_LDA(At, 0, 1); PG8_STAGE(PG8_SB(0, 0), b2, voffB); PG8_STAGE(PG8_SB(0, 1), b2 + hstepB, voffB); PG8_STAGE(PG8_SA(0, 0), a2, voffA);
;             PG8_WAIT_V(8); PG8_WAIT_L(0); PG8_BAR; PG8_MMA(1, 0, At, B0); PG8_MMA(1, 1, At, B1); PG8_BAR; PG8_SCHED;
.LBB0_928:
	s_ashr_i32 s12, s40, 5
	s_ashr_i32 s13, s12, 31
	s_lshl_b64 s[12:13], s[12:13], 24
	v_readlane_b32 s14, v235, 38
	v_readlane_b32 s15, v235, 39
	s_add_u32 s11, s14, s12
	s_addc_u32 s13, s15, s13
	s_lshl_b32 s12, s40, 19
	s_and_b32 s12, s12, 0xf80000
	s_add_u32 s12, s11, s12
	s_addc_u32 s13, s13, 0
	s_and_b64 s[14:15], s[4:5], exec
	s_cselect_b32 s43, s13, s17
	s_cselect_b32 s44, s12, s16
	s_ashr_i32 s11, s10, 31
	s_lshl_b64 s[14:15], s[10:11], 19
	v_readlane_b32 s18, v235, 31
	v_readlane_b32 s19, v235, 32
	s_add_u32 s14, s18, s14
	s_addc_u32 s15, s19, s15
	s_and_b64 s[18:19], s[4:5], exec
	s_cselect_b32 s11, s15, s3
	s_cselect_b32 s45, s14, s2
	s_add_u32 s16, s16, 0x40080
	s_addc_u32 s17, s17, 0
	s_add_u32 s46, s2, 0x100
	s_addc_u32 s47, s3, 0
	s_mov_b32 s48, -2
	s_lshl_b32 s60, s41, 14
	s_add_u32 s58, s56, s60
	s_addc_u32 s59, s57, 0
	s_sub_i32 s60, 0x24000, s58
	s_lshl_b32 s62, s22, 1
	s_add_u32 s58, s58, s62
	s_addc_u32 s59, s59, 0
	s_waitcnt vmcnt(0)
	ds_read_b128 v[146:149], v153
	ds_read_b128 v[160:163], v153 offset:1024
	ds_read_b128 v[164:167], v153 offset:2048
	ds_read_b128 v[168:171], v153 offset:3072
	ds_read_b128 v[172:175], v154
	ds_read_b128 v[176:179], v154 offset:1024
	ds_read_b128 v[180:183], v154 offset:2048
	ds_read_b128 v[184:187], v154 offset:3072
	s_add_u32 s2, s16, 0xfffc0080
	s_addc_u32 s3, s17, -1
	s_cmp_eq_u32 s48, 12
	s_cselect_b32 s19, s43, s3
	s_cselect_b32 s18, s44, s2
	s_cselect_b32 s3, s11, s47
	s_cselect_b32 s2, s45, s46
	v_lshl_add_u64 v[194:195], s[16:17], 0, v[140:141]
	s_add_i32 m0, s22, 0xc000
	ds_read_b128 v[190:193], v155
	ds_read_b128 v[198:201], v155 offset:1024
	ds_read_b128 v[202:205], v155 offset:2048
	ds_read_b128 v[206:209], v155 offset:3072
	ds_read_b128 v[210:213], v155 offset:4096
	ds_read_b128 v[214:217], v155 offset:5120
	ds_read_b128 v[218:221], v155 offset:6144
	ds_read_b128 v[222:225], v155 offset:7168
	global_load_lds_dwordx4 v[194:195], off
	v_lshl_add_u64 v[194:195], s[16:17], 0, v[142:143]
	s_add_i32 m0, s22, 0xe000
	s_nop 0
	global_load_lds_dwordx4 v[194:195], off
	s_waitcnt vmcnt(8)
	s_waitcnt lgkmcnt(0)
	s_barrier
	s_waitcnt lgkmcnt(0)
	v_mfma_f32_16x16x32_bf16 v[124:127], v[146:149], v[190:193], 0
	v_mfma_f32_16x16x32_bf16 v[116:119], v[164:167], v[190:193], 0
	v_mfma_f32_16x16x32_bf16 v[108:111], v[146:149], v[202:205], 0
	v_mfma_f32_16x16x32_bf16 v[100:103], v[164:167], v[202:205], 0
	v_mfma_f32_16x16x32_bf16 v[92:95], v[146:149], v[210:213], 0
	v_mfma_f32_16x16x32_bf16 v[84:87], v[164:167], v[210:213], 0
	v_mfma_f32_16x16x32_bf16 v[76:79], v[146:149], v[218:221], 0
	v_mfma_f32_16x16x32_bf16 v[68:71], v[164:167], v[218:221], 0
	v_mfma_f32_16x16x32_bf16 v[124:127], v[160:163], v[198:201], v[124:127]
	v_mfma_f32_16x16x32_bf16 v[116:119], v[168:171], v[198:201], v[116:119]
	v_mfma_f32_16x16x32_bf16 v[108:111], v[160:163], v[206:209], v[108:111]
	v_mfma_f32_16x16x32_bf16 v[100:103], v[168:171], v[206:209], v[100:103]
	v_mfma_f32_16x16x32_bf16 v[92:95], v[160:163], v[214:217], v[92:95]
	v_mfma_f32_16x16x32_bf16 v[84:87], v[168:171], v[214:217], v[84:87]
	v_mfma_f32_16x16x32_bf16 v[76:79], v[160:163], v[222:225], v[76:79]
	v_mfma_f32_16x16x32_bf16 v[68:71], v[168:171], v[222:225], v[68:71]
	v_mfma_f32_16x16x32_bf16 v[120:123], v[172:175], v[190:193], 0
	v_mfma_f32_16x16x32_bf16 v[112:115], v[180:183], v[190:193], 0
	v_mfma_f32_16x16x32_bf16 v[104:107], v[172:175], v[202:205], 0
	v_mfma_f32_16x16x32_bf16 v[96:99], v[180:183], v[202:205], 0
	v_mfma_f32_16x16x32_bf16 v[88:91], v[172:175], v[210:213], 0
	v_mfma_f32_16x16x32_bf16 v[80:83], v[180:183], v[210:213], 0
	v_mfma_f32_16x16x32_bf16 v[72:75], v[172:175], v[218:221], 0
	v_mfma_f32_16x16x32_bf16 v[64:67], v[180:183], v[218:221], 0
	v_mfma_f32_16x16x32_bf16 v[120:123], v[176:179], v[198:201], v[120:123]
	v_mfma_f32_16x16x32_bf16 v[112:115], v[184:187], v[198:201], v[112:115]
	v_mfma_f32_16x16x32_bf16 v[104:107], v[176:179], v[206:209], v[104:107]
	v_mfma_f32_16x16x32_bf16 v[96:99], v[184:187], v[206:209], v[96:99]
	v_mfma_f32_16x16x32_bf16 v[88:91], v[176:179], v[214:217], v[88:91]
	v_mfma_f32_16x16x32_bf16 v[80:83], v[184:187], v[214:217], v[80:83]
	v_mfma_f32_16x16x32_bf16 v[72:75], v[176:179], v[222:225], v[72:75]
	v_mfma_f32_16x16x32_bf16 v[64:67], v[184:187], v[222:225], v[64:67]
	s_barrier
	s_mov_b32 m0, s61
	s_nop 0
	global_load_lds_dwordx4 v238, s[58:59]
	global_load_lds_dwordx4 v238, s[58:59] offset:1024
	s_add_i32 s49, s35, s20
	v_lshl_add_u64 v[194:195], s[2:3], 0, v[132:133]
	s_mov_b32 m0, s49
	ds_read_b128 v[190:193], v155 offset:16384
	ds_read_b128 v[198:201], v155 offset:17408
	ds_read_b128 v[202:205], v155 offset:18432
	ds_read_b128 v[206:209], v155 offset:19456
	ds_read_b128 v[210:213], v155 offset:20480
	ds_read_b128 v[214:217], v155 offset:21504
	ds_read_b128 v[218:221], v155 offset:22528
	ds_read_b128 v[222:225], v155 offset:23552
	global_load_lds_dwordx4 v[194:195], off
	s_add_i32 m0, s49, 0x2000
	s_add_u32 s50, s2, 0x40000
	v_lshl_add_u64 v[226:227], s[2:3], 0, v[128:129]
	s_addc_u32 s51, s3, 0
	s_add_i32 s49, s36, s20
	global_load_lds_dwordx4 v[226:227], off
	v_lshl_add_u64 v[228:229], s[50:51], 0, v[132:133]
	s_mov_b32 m0, s49
	v_lshl_add_u64 v[230:231], s[18:19], 0, v[130:131]
	global_load_lds_dwordx4 v[228:229], off
	v_lshl_add_u64 v[228:229], s[50:51], 0, v[128:129]
	s_add_i32 m0, s49, 0x2000
	s_nop 0
	global_load_lds_dwordx4 v[228:229], off
	v_lshl_add_u64 v[228:229], s[18:19], 0, v[134:135]
	s_mov_b32 m0, s22
	s_nop 0
	global_load_lds_dwordx4 v[228:229], off
	s_mov_b32 m0, s23
	s_nop 0
	global_load_lds_dwordx4 v[230:231], off
	s_waitcnt vmcnt(8)
	s_waitcnt lgkmcnt(0)
	s_barrier
; #define PG8_STAGE(bufoff, gbase, voff) do { _Pragma("unroll") for (int _i = 0; _i < 2; ++_i) \
;         __builtin_amdgcn_global_load_lds((const unsigned*)((const char*)(gbase) + (voff)[_i]), (LAS unsigned*)(lds + (bufoff) + ldsw + _i * 8192), 16, 0, 0); } while (0)
; #define PG8_LDA(dst, b, h) do { _Pragma("unroll") for (int m = 0; m < 4; ++m) _Pragma("unroll") for (int k = 0; k < 2; ++k) dst[m][k] = *(const LAS bf16x8*)(lds + PG8_SA(b, h) + aoff + m * 2048 + k * 1024); } while (0)
; #define PG8_LDB(dst, b, h) do { _Pragma("unroll") for (int n = 0; n < 2; ++n) _Pragma("unroll") for (int k = 0; k < 2; ++k) dst[n][k] = *(const LAS bf16x8*)(lds + PG8_SB(b, h) + boff + n * 2048 + k * 1024); } while (0)
; #define PG8_MMA(ai, bj, At, Bt) do { __builtin_amdgcn_s_setprio(1); _Pragma("unroll") for (int m = 0; m < 4; ++m) _Pragma("unroll") for (int n = 0; n < 2; ++n) _Pragma("unroll") for (int k = 0; k < 2; ++k) \
;         acc[ai][bj][m][n] = __builtin_amdgcn_mfma_f32_16x16x32_bf16(Bt[n][k], At[m][k], acc[ai][bj][m][n], 0, 0, 0); __builtin_amdgcn_s_setprio(0); } while (0)
; #define PG8_WAIT_V(n) asm volatile("s_waitcnt vmcnt(" #n ")" ::: "memory")
; #define PG8_WAIT_L(n) asm volatile("s_waitcnt lgkmcnt(" #n ")" ::: "memory")
; #define PG8_BAR __builtin_amdgcn_s_barrier()
; #define PG8_SCHED __builtin_amdgcn_sched_barrier(0)
; template <class Epi>
; __device__ __forceinline__ void gemm_phase(LAS unsigned char* lds, const Gemm g, const StaticOrder& S, const Epi& E) {
;     ...
;             PG8_WAIT_V(8); PG8_WAIT_L(0); PG8_BAR; PG8_MMA(1, 0, At, B0); PG8_MMA(1, 1, At, B1); PG8_BAR; PG8_SCHED;
;             PG8_LDB(B0, 1, 0); PG8_LDB(B1, 1, 1); PG8_SCHED; PG8_LDA(At, 1, 0); PG8_STAGE(PG8_SA(0, 1), a2 + hstepA, voffA);
;             PG8_WAIT_V(8); PG8_WAIT_L(0); PG8_BAR; PG8_MMA(0, 0, At, B0); PG8_MMA(0, 1, At, B1); PG8_BAR; PG8_SCHED;
;             PG8_LDA(At, 1, 1); PG8_STAGE(PG8_SB(1, 0), b3, voffB); PG8_STAGE(PG8_SB(1, 1), b3 + hstepB, voffB); PG8_STAGE(PG8_SA(1, 0), a3, voffA);
	s_waitcnt lgkmcnt(0)
	v_mfma_f32_16x16x32_bf16 v[60:63], v[146:149], v[190:193], 0
	v_mfma_f32_16x16x32_bf16 v[52:55], v[164:167], v[190:193], 0
	v_mfma_f32_16x16x32_bf16 v[44:47], v[146:149], v[202:205], 0
	v_mfma_f32_16x16x32_bf16 v[36:39], v[164:167], v[202:205], 0
	v_mfma_f32_16x16x32_bf16 v[28:31], v[146:149], v[210:213], 0
	v_mfma_f32_16x16x32_bf16 v[20:23], v[164:167], v[210:213], 0
	v_mfma_f32_16x16x32_bf16 v[12:15], v[146:149], v[218:221], 0
	v_mfma_f32_16x16x32_bf16 v[4:7], v[164:167], v[218:221], 0
	v_mfma_f32_16x16x32_bf16 v[60:63], v[160:163], v[198:201], v[60:63]
	v_mfma_f32_16x16x32_bf16 v[52:55], v[168:171], v[198:201], v[52:55]
	v_mfma_f32_16x16x32_bf16 v[44:47], v[160:163], v[206:209], v[44:47]
	v_mfma_f32_16x16x32_bf16 v[36:39], v[168:171], v[206:209], v[36:39]
	v_mfma_f32_16x16x32_bf16 v[28:31], v[160:163], v[214:217], v[28:31]
	v_mfma_f32_16x16x32_bf16 v[20:23], v[168:171], v[214:217], v[20:23]
	v_mfma_f32_16x16x32_bf16 v[12:15], v[160:163], v[222:225], v[12:15]
	v_mfma_f32_16x16x32_bf16 v[4:7], v[168:171], v[222:225], v[4:7]
	v_mfma_f32_16x16x32_bf16 v[56:59], v[172:175], v[190:193], 0
	v_mfma_f32_16x16x32_bf16 v[48:51], v[180:183], v[190:193], 0
	v_mfma_f32_16x16x32_bf16 v[40:43], v[172:175], v[202:205], 0
	v_mfma_f32_16x16x32_bf16 v[32:35], v[180:183], v[202:205], 0
	v_mfma_f32_16x16x32_bf16 v[24:27], v[172:175], v[210:213], 0
	v_mfma_f32_16x16x32_bf16 v[16:19], v[180:183], v[210:213], 0
	v_mfma_f32_16x16x32_bf16 v[8:11], v[172:175], v[218:221], 0
	v_mfma_f32_16x16x32_bf16 v[0:3], v[180:183], v[218:221], 0
	v_mfma_f32_16x16x32_bf16 v[56:59], v[176:179], v[198:201], v[56:59]
	v_mfma_f32_16x16x32_bf16 v[48:51], v[184:187], v[198:201], v[48:51]
	v_mfma_f32_16x16x32_bf16 v[40:43], v[176:179], v[206:209], v[40:43]
	v_mfma_f32_16x16x32_bf16 v[32:35], v[184:187], v[206:209], v[32:35]
	v_mfma_f32_16x16x32_bf16 v[24:27], v[176:179], v[214:217], v[24:27]
	v_mfma_f32_16x16x32_bf16 v[16:19], v[184:187], v[214:217], v[16:19]
	v_mfma_f32_16x16x32_bf16 v[8:11], v[176:179], v[222:225], v[8:11]
	v_mfma_f32_16x16x32_bf16 v[0:3], v[184:187], v[222:225], v[0:3]
	s_barrier
	s_add_i32 s49, 0, 0x18000
	v_add_u32_e32 v136, s49, v151
	s_add_i32 s50, 0, 0x1c000
	ds_read_b128 v[146:149], v136
	ds_read_b128 v[160:163], v136 offset:1024
	ds_read_b128 v[164:167], v136 offset:2048
	ds_read_b128 v[168:171], v136 offset:3072
	v_add_u32_e32 v136, s50, v151
	ds_read_b128 v[172:175], v136
	ds_read_b128 v[176:179], v136 offset:1024
	ds_read_b128 v[180:183], v136 offset:2048
	ds_read_b128 v[184:187], v136 offset:3072
	s_add_u32 s18, s18, 0x40000
	s_addc_u32 s19, s19, 0
	s_mov_b32 m0, s24
	v_lshl_add_u64 v[232:233], s[18:19], 0, v[134:135]
	ds_read_b128 v[190:193], v155 offset:32768
	ds_read_b128 v[198:201], v155 offset:33792
	ds_read_b128 v[202:205], v155 offset:34816
	ds_read_b128 v[206:209], v155 offset:35840
	ds_read_b128 v[210:213], v155 offset:36864
	ds_read_b128 v[214:217], v155 offset:37888
	ds_read_b128 v[218:221], v155 offset:38912
	ds_read_b128 v[222:225], v155 offset:39936
	global_load_lds_dwordx4 v[232:233], off
	v_lshl_add_u64 v[232:233], s[18:19], 0, v[130:131]
	s_mov_b32 m0, s25
	s_nop 0
	global_load_lds_dwordx4 v[232:233], off
	s_waitcnt vmcnt(8)
	s_waitcnt lgkmcnt(0)
	s_barrier
	s_waitcnt lgkmcnt(0)
	v_mfma_f32_16x16x32_bf16 v[124:127], v[146:149], v[190:193], v[124:127]
	v_mfma_f32_16x16x32_bf16 v[116:119], v[164:167], v[190:193], v[116:119]
	v_mfma_f32_16x16x32_bf16 v[108:111], v[146:149], v[202:205], v[108:111]
	v_mfma_f32_16x16x32_bf16 v[100:103], v[164:167], v[202:205], v[100:103]
	v_mfma_f32_16x16x32_bf16 v[92:95], v[146:149], v[210:213], v[92:95]
	v_mfma_f32_16x16x32_bf16 v[84:87], v[164:167], v[210:213], v[84:87]
	v_mfma_f32_16x16x32_bf16 v[76:79], v[146:149], v[218:221], v[76:79]
	v_mfma_f32_16x16x32_bf16 v[68:71], v[164:167], v[218:221], v[68:71]
	v_mfma_f32_16x16x32_bf16 v[124:127], v[160:163], v[198:201], v[124:127]
	v_mfma_f32_16x16x32_bf16 v[116:119], v[168:171], v[198:201], v[116:119]
	v_mfma_f32_16x16x32_bf16 v[108:111], v[160:163], v[206:209], v[108:111]
	v_mfma_f32_16x16x32_bf16 v[100:103], v[168:171], v[206:209], v[100:103]
	v_mfma_f32_16x16x32_bf16 v[92:95], v[160:163], v[214:217], v[92:95]
	v_mfma_f32_16x16x32_bf16 v[84:87], v[168:171], v[214:217], v[84:87]
	v_mfma_f32_16x16x32_bf16 v[76:79], v[160:163], v[222:225], v[76:79]
	v_mfma_f32_16x16x32_bf16 v[68:71], v[168:171], v[222:225], v[68:71]
	v_mfma_f32_16x16x32_bf16 v[120:123], v[172:175], v[190:193], v[120:123]
	v_mfma_f32_16x16x32_bf16 v[112:115], v[180:183], v[190:193], v[112:115]
	v_mfma_f32_16x16x32_bf16 v[104:107], v[172:175], v[202:205], v[104:107]
	v_mfma_f32_16x16x32_bf16 v[96:99], v[180:183], v[202:205], v[96:99]
	v_mfma_f32_16x16x32_bf16 v[88:91], v[172:175], v[210:213], v[88:91]
	v_mfma_f32_16x16x32_bf16 v[80:83], v[180:183], v[210:213], v[80:83]
	v_mfma_f32_16x16x32_bf16 v[72:75], v[172:175], v[218:221], v[72:75]
	v_mfma_f32_16x16x32_bf16 v[64:67], v[180:183], v[218:221], v[64:67]
	v_mfma_f32_16x16x32_bf16 v[120:123], v[176:179], v[198:201], v[120:123]
	v_mfma_f32_16x16x32_bf16 v[112:115], v[184:187], v[198:201], v[112:115]
	v_mfma_f32_16x16x32_bf16 v[104:107], v[176:179], v[206:209], v[104:107]
	v_mfma_f32_16x16x32_bf16 v[96:99], v[184:187], v[206:209], v[96:99]
	v_mfma_f32_16x16x32_bf16 v[88:91], v[176:179], v[214:217], v[88:91]
	v_mfma_f32_16x16x32_bf16 v[80:83], v[184:187], v[214:217], v[80:83]
	v_mfma_f32_16x16x32_bf16 v[72:75], v[176:179], v[222:225], v[72:75]
	v_mfma_f32_16x16x32_bf16 v[64:67], v[184:187], v[222:225], v[64:67]
	s_barrier
; #define PG8_STAGE(bufoff, gbase, voff) do { _Pragma("unroll") for (int _i = 0; _i < 2; ++_i) \
;         __builtin_amdgcn_global_load_lds((const unsigned*)((const char*)(gbase) + (voff)[_i]), (LAS unsigned*)(lds + (bufoff) + ldsw + _i * 8192), 16, 0, 0); } while (0)
; #define PG8_LDA(dst, b, h) do { _Pragma("unroll") for (int m = 0; m < 4; ++m) _Pragma("unroll") for (int k = 0; k < 2; ++k) dst[m][k] = *(const LAS bf16x8*)(lds + PG8_SA(b, h) + aoff + m * 2048 + k * 1024); } while (0)
; #define PG8_MMA(ai, bj, At, Bt) do { __builtin_amdgcn_s_setprio(1); _Pragma("unroll") for (int m = 0; m < 4; ++m) _Pragma("unroll") for (int n = 0; n < 2; ++n) _Pragma("unroll") for (int k = 0; k < 2; ++k) \
;         acc[ai][bj][m][n] = __builtin_amdgcn_mfma_f32_16x16x32_bf16(Bt[n][k], At[m][k], acc[ai][bj][m][n], 0, 0, 0); __builtin_amdgcn_s_setprio(0); } while (0)
; #define PG8_WAIT_V(n) asm volatile("s_waitcnt vmcnt(" #n ")" ::: "memory")
; #define PG8_WAIT_L(n) asm volatile("s_waitcnt lgkmcnt(" #n ")" ::: "memory")
; #define PG8_BAR __builtin_amdgcn_s_barrier()
; #define PG8_SCHED __builtin_amdgcn_sched_barrier(0)
; template <class Epi>
; __device__ __forceinline__ void gemm_phase(LAS unsigned char* lds, const Gemm g, const StaticOrder& S, const Epi& E) {
;     ...
;             PG8_LDA(At, 1, 1); PG8_STAGE(PG8_SB(1, 0), b3, voffB); PG8_STAGE(PG8_SB(1, 1), b3 + hstepB, voffB); PG8_STAGE(PG8_SA(1, 0), a3, voffA);
;             PG8_WAIT_V(8); PG8_WAIT_L(0); PG8_BAR; PG8_MMA(1, 0, At, B0); PG8_MMA(1, 1, At, B1); PG8_BAR; PG8_SCHED;
;         }
	s_add_i32 s18, s49, s20
	v_lshl_add_u64 v[194:195], v[194:195], 0, s[6:7]
	s_mov_b32 m0, s18
	ds_read_b128 v[190:193], v155 offset:49152
	ds_read_b128 v[198:201], v155 offset:50176
	ds_read_b128 v[202:205], v155 offset:51200
	ds_read_b128 v[206:209], v155 offset:52224
	ds_read_b128 v[210:213], v155 offset:53248
	ds_read_b128 v[214:217], v155 offset:54272
	ds_read_b128 v[218:221], v155 offset:55296
	ds_read_b128 v[222:225], v155 offset:56320
	global_load_lds_dwordx4 v[194:195], off
	s_add_i32 m0, s18, 0x2000
	s_add_u32 s2, s2, 0x40080
	v_lshl_add_u64 v[194:195], v[226:227], 0, s[6:7]
	s_addc_u32 s3, s3, 0
	s_add_i32 s18, s50, s20
	global_load_lds_dwordx4 v[194:195], off
	v_lshl_add_u64 v[194:195], s[2:3], 0, v[132:133]
	s_mov_b32 m0, s18
	s_nop 0
	global_load_lds_dwordx4 v[194:195], off
	v_lshl_add_u64 v[194:195], s[2:3], 0, v[128:129]
	s_add_i32 m0, s18, 0x2000
	s_nop 0
	global_load_lds_dwordx4 v[194:195], off
	v_lshl_add_u64 v[194:195], v[228:229], 0, s[6:7]
	s_mov_b32 m0, s30
	s_nop 0
	global_load_lds_dwordx4 v[194:195], off
	v_lshl_add_u64 v[194:195], v[230:231], 0, s[6:7]
	s_mov_b32 m0, s31
	s_nop 0
	global_load_lds_dwordx4 v[194:195], off
	s_waitcnt vmcnt(8)
	s_waitcnt lgkmcnt(0)
	s_barrier
	s_waitcnt lgkmcnt(0)
	v_mfma_f32_16x16x32_bf16 v[60:63], v[146:149], v[190:193], v[60:63]
	v_mfma_f32_16x16x32_bf16 v[52:55], v[164:167], v[190:193], v[52:55]
	v_mfma_f32_16x16x32_bf16 v[44:47], v[146:149], v[202:205], v[44:47]
	v_mfma_f32_16x16x32_bf16 v[36:39], v[164:167], v[202:205], v[36:39]
	v_mfma_f32_16x16x32_bf16 v[28:31], v[146:149], v[210:213], v[28:31]
	v_mfma_f32_16x16x32_bf16 v[20:23], v[164:167], v[210:213], v[20:23]
	v_mfma_f32_16x16x32_bf16 v[12:15], v[146:149], v[218:221], v[12:15]
	v_mfma_f32_16x16x32_bf16 v[4:7], v[164:167], v[218:221], v[4:7]
	v_mfma_f32_16x16x32_bf16 v[60:63], v[160:163], v[198:201], v[60:63]
	v_mfma_f32_16x16x32_bf16 v[52:55], v[168:171], v[198:201], v[52:55]
	v_mfma_f32_16x16x32_bf16 v[44:47], v[160:163], v[206:209], v[44:47]
	v_mfma_f32_16x16x32_bf16 v[36:39], v[168:171], v[206:209], v[36:39]
	v_mfma_f32_16x16x32_bf16 v[28:31], v[160:163], v[214:217], v[28:31]
	v_mfma_f32_16x16x32_bf16 v[20:23], v[168:171], v[214:217], v[20:23]
	v_mfma_f32_16x16x32_bf16 v[12:15], v[160:163], v[222:225], v[12:15]
	v_mfma_f32_16x16x32_bf16 v[4:7], v[168:171], v[222:225], v[4:7]
	v_mfma_f32_16x16x32_bf16 v[56:59], v[172:175], v[190:193], v[56:59]
	v_mfma_f32_16x16x32_bf16 v[48:51], v[180:183], v[190:193], v[48:51]
	v_mfma_f32_16x16x32_bf16 v[40:43], v[172:175], v[202:205], v[40:43]
	v_mfma_f32_16x16x32_bf16 v[32:35], v[180:183], v[202:205], v[32:35]
	v_mfma_f32_16x16x32_bf16 v[24:27], v[172:175], v[210:213], v[24:27]
	v_mfma_f32_16x16x32_bf16 v[16:19], v[180:183], v[210:213], v[16:19]
	v_mfma_f32_16x16x32_bf16 v[8:11], v[172:175], v[218:221], v[8:11]
	v_mfma_f32_16x16x32_bf16 v[0:3], v[180:183], v[218:221], v[0:3]
	v_mfma_f32_16x16x32_bf16 v[56:59], v[176:179], v[198:201], v[56:59]
	v_mfma_f32_16x16x32_bf16 v[48:51], v[184:187], v[198:201], v[48:51]
	v_mfma_f32_16x16x32_bf16 v[40:43], v[176:179], v[206:209], v[40:43]
	v_mfma_f32_16x16x32_bf16 v[32:35], v[184:187], v[206:209], v[32:35]
	v_mfma_f32_16x16x32_bf16 v[24:27], v[176:179], v[214:217], v[24:27]
	v_mfma_f32_16x16x32_bf16 v[16:19], v[184:187], v[214:217], v[16:19]
	v_mfma_f32_16x16x32_bf16 v[8:11], v[176:179], v[222:225], v[8:11]
	v_mfma_f32_16x16x32_bf16 v[0:3], v[184:187], v[222:225], v[0:3]
	s_barrier
	s_add_i32 s48, s48, 2
	s_add_u32 s16, s16, 0x100
	s_addc_u32 s17, s17, 0
	s_add_u32 s46, s46, 0x100
	s_addc_u32 s47, s47, 0
	s_cmp_gt_u32 s48, 13
	s_cbranch_scc0 .LBB0_929

; template <int NP> __device__ __forceinline__ void load_rs(const float* ssp, int row0, int fq, float (&rs)[2][4]) {
;     ...
;         f32x4 p[2][4];
; #pragma unroll
;         for (int ai = 0; ai < 2; ++ai)
; #pragma unroll
;             for (int m = 0; m < 4; ++m) p[ai][m] = *(const f32x4*)(ssp + (size_t)(row0 + ai * HALF + m * 16) * 16 + 4 * fq);
; #pragma unroll
;         for (int ai = 0; ai < 2; ++ai)
; #pragma unroll
;             for (int m = 0; m < 4; ++m) { float s = (p[ai][m][0] + p[ai][m][1]) + (p[ai][m][2] + p[ai][m][3]); s += __shfl_xor(s, 16); s += __shfl_xor(s, 32); rs[ai][m] = s; }
;     }
; #pragma unroll
;     for (int ai = 0; ai < 2; ++ai)
; #pragma unroll
;         for (int m = 0; m < 4; ++m) rs[ai][m] = __builtin_amdgcn_rsqf(rs[ai][m] * (1.0f / D_MODEL) + RMS_EPS);
;     __device__ __forceinline__ void operator()(const f32x4 (&acc)[2][2][4][2], const Unit& u, int wr, int wc, int fr, int fq) const {
;         const int row0 = u.pm * BM + wr * 64 + fr, col0 = u.pn * HALF + wc * 32 + 8 * fq;
;         float rs[2][4]; load_rs<NP>(ssp, row0, fq, rs);
; #pragma unroll
;         for (int ai = 0; ai < 2; ++ai)
; #pragma unroll
;             for (int m = 0; m < 4; ++m) {
;                 const int row = row0 + ai * HALF + m * 16; const float r = rs[ai][m];
;                 const float nrl = r * -1.44269504089f, r2 = r * r;
.LBB0_932:
	s_lshl_b32 s2, s41, 8
	s_add_i32 s2, s2, s29
	v_or_b32_e32 v146, s2, v150
	v_ashrrev_i32_e32 v147, 31, v146
	v_or_b32_e32 v160, 16, v146
	v_lshlrev_b64 v[148:149], 6, v[146:147]
	v_ashrrev_i32_e32 v161, 31, v160
	v_or_b32_e32 v168, 32, v146
	v_or_b32_e32 v170, 48, v146
	v_add_u32_e32 v146, 0x80, v146
	v_lshlrev_b64 v[160:161], 6, v[160:161]
	v_ashrrev_i32_e32 v169, 31, v168
	v_ashrrev_i32_e32 v171, 31, v170
	v_ashrrev_i32_e32 v147, 31, v146
	v_lshl_add_u64 v[148:149], v[138:139], 0, v[148:149]
	v_lshl_add_u64 v[164:165], v[138:139], 0, v[160:161]
	v_lshlrev_b64 v[168:169], 6, v[168:169]
	v_lshlrev_b64 v[170:171], 6, v[170:171]
	v_lshlrev_b64 v[176:177], 6, v[146:147]
	v_add_u32_e32 v148, s60, v148
	ds_read_b128 v[160:163], v148
	s_nop 0
	v_add_u32_e32 v164, s60, v164
	ds_read_b128 v[164:167], v164
	v_lshl_add_u64 v[168:169], v[138:139], 0, v[168:169]
	v_lshl_add_u64 v[172:173], v[138:139], 0, v[170:171]
	v_lshl_add_u64 v[176:177], v[138:139], 0, v[176:177]
	v_add_u32_e32 v168, s60, v168
	ds_read_b128 v[168:171], v168
	s_nop 0
	v_add_u32_e32 v172, s60, v172
	ds_read_b128 v[172:175], v172
	v_add_co_u32_e32 v148, vcc, s26, v148
	v_add_u32_e32 v176, s60, v176
	ds_read_b128 v[176:179], v176
	s_nop 0
	v_addc_co_u32_e32 v149, vcc, 0, v149, vcc
	ds_read_b128 v[180:183], v148 offset:1024
	ds_read_b128 v[184:187], v148 offset:2048
	ds_read_b128 v[190:193], v148 offset:3072
	v_and_b32_e32 v147, 64, v156
	v_xor_b32_e32 v136, 16, v156
	v_add_u32_e32 v147, 64, v147
	v_xor_b32_e32 v149, 32, v156
	v_cmp_lt_i32_e32 vcc, v136, v147
	v_pk_mul_f32 v[120:121], v[124:125], v[120:121]
	v_pk_mul_f32 v[122:123], v[126:127], v[122:123]
	v_cndmask_b32_e32 v136, v156, v136, vcc
	v_cmp_lt_i32_e32 vcc, v149, v147
	v_lshlrev_b32_e32 v136, 2, v136
	v_pk_mul_f32 v[112:113], v[116:117], v[112:113]
	v_cndmask_b32_e32 v147, v156, v149, vcc
	v_lshlrev_b32_e32 v147, 2, v147
	v_pk_mul_f32 v[114:115], v[118:119], v[114:115]
	v_pk_mul_f32 v[104:105], v[108:109], v[104:105]
	s_ashr_i32 s3, s2, 13
	s_mul_hi_i32 s11, s3, 0x4400000
	s_mul_i32 s3, s3, 0x4400000
	v_readlane_b32 s16, v235, 44
	v_lshl_or_b32 v148, s42, 7, v152
	v_readlane_b32 s17, v235, 45
	v_pk_mul_f32 v[106:107], v[110:111], v[106:107]
	v_pk_mul_f32 v[96:97], v[100:101], v[96:97]
	v_pk_mul_f32 v[98:99], v[102:103], v[98:99]
	v_pk_mul_f32 v[88:89], v[92:93], v[88:89]
	v_pk_mul_f32 v[90:91], v[94:95], v[90:91]
	v_pk_mul_f32 v[80:81], v[84:85], v[80:81]
	v_pk_mul_f32 v[82:83], v[86:87], v[82:83]
	v_pk_mul_f32 v[72:73], v[76:77], v[72:73]
	v_pk_mul_f32 v[74:75], v[78:79], v[74:75]
	v_pk_mul_f32 v[64:65], v[68:69], v[64:65]
	v_pk_mul_f32 v[66:67], v[70:71], v[66:67]
	v_pk_mul_f32 v[56:57], v[60:61], v[56:57]
	v_pk_mul_f32 v[58:59], v[62:63], v[58:59]
	v_pk_mul_f32 v[48:49], v[52:53], v[48:49]
	v_pk_mul_f32 v[50:51], v[54:55], v[50:51]
	v_pk_mul_f32 v[40:41], v[44:45], v[40:41]
	v_pk_mul_f32 v[42:43], v[46:47], v[42:43]
	v_pk_mul_f32 v[32:33], v[36:37], v[32:33]
	v_pk_mul_f32 v[34:35], v[38:39], v[34:35]
	v_pk_mul_f32 v[24:25], v[28:29], v[24:25]
	v_pk_mul_f32 v[26:27], v[30:31], v[26:27]
	v_pk_mul_f32 v[16:17], v[20:21], v[16:17]
	v_pk_mul_f32 v[18:19], v[22:23], v[18:19]
	v_pk_mul_f32 v[8:9], v[12:13], v[8:9]
	v_pk_mul_f32 v[10:11], v[14:15], v[10:11]
	v_pk_mul_f32 v[0:1], v[4:5], v[0:1]
	v_pk_mul_f32 v[2:3], v[6:7], v[2:3]
	s_waitcnt lgkmcnt(0)
	v_mov_b32_e32 v194, v161
	v_mov_b32_e32 v195, v162
	v_mov_b32_e32 v161, v163
	v_pk_add_f32 v[160:161], v[194:195], v[160:161]
	v_mov_b32_e32 v162, v165
	v_mov_b32_e32 v163, v166
	v_mov_b32_e32 v165, v167
	v_mov_b32_e32 v166, v169
	v_mov_b32_e32 v167, v170
	v_mov_b32_e32 v169, v171
	v_mov_b32_e32 v170, v173
	v_mov_b32_e32 v171, v174
	v_mov_b32_e32 v173, v175
	v_mov_b32_e32 v174, v177
	v_mov_b32_e32 v175, v178
	v_mov_b32_e32 v177, v179
	v_add_f32_e32 v149, v160, v161
	v_pk_add_f32 v[160:161], v[162:163], v[164:165]
	v_pk_add_f32 v[162:163], v[166:167], v[168:169]
	v_pk_add_f32 v[166:167], v[174:175], v[176:177]
	v_add_f32_e32 v160, v160, v161
	v_add_f32_e32 v161, v162, v163
	v_mov_b32_e32 v236, v149
	v_mov_b32_e32 v237, v149
	s_nop 1
	v_permlane16_swap_b32_e32 v236, v237
	v_cndmask_b32_e64 v159, v237, v236, s[98:99]
	v_add_f32_e32 v163, v166, v167
	v_mov_b32_e32 v236, v160
	v_mov_b32_e32 v237, v160
	s_nop 1
	v_permlane16_swap_b32_e32 v236, v237
	v_cndmask_b32_e64 v166, v237, v236, s[98:99]
	v_mov_b32_e32 v236, v161
	v_mov_b32_e32 v237, v161
	s_nop 1
	v_permlane16_swap_b32_e32 v236, v237
	v_cndmask_b32_e64 v167, v237, v236, s[98:99]
	v_mov_b32_e32 v178, v181
	s_waitcnt lgkmcnt(2)
	v_add_f32_e32 v149, v149, v159
	v_mov_b32_e32 v236, v149
	v_mov_b32_e32 v237, v149
	s_nop 1
	v_permlane32_swap_b32_e32 v236, v237
	v_cndmask_b32_e64 v159, v237, v236, s[100:101]
	s_waitcnt lgkmcnt(2)
	v_add_f32_e32 v160, v160, v166
	s_waitcnt lgkmcnt(1)
	v_add_f32_e32 v161, v161, v167
	v_mov_b32_e32 v236, v160
	v_mov_b32_e32 v237, v160
	s_nop 1
	v_permlane32_swap_b32_e32 v236, v237
	v_cndmask_b32_e64 v166, v237, v236, s[100:101]
	v_mov_b32_e32 v236, v161
	v_mov_b32_e32 v237, v161
	s_nop 1
	v_permlane32_swap_b32_e32 v236, v237
	v_cndmask_b32_e64 v167, v237, v236, s[100:101]
	v_mov_b32_e32 v179, v182
	v_mov_b32_e32 v181, v183
	v_mov_b32_e32 v182, v185
	v_mov_b32_e32 v183, v186
	v_mov_b32_e32 v185, v187
	v_mov_b32_e32 v186, v191
	v_mov_b32_e32 v187, v192
	v_mov_b32_e32 v191, v193
	v_pk_add_f32 v[164:165], v[170:171], v[172:173]
	v_pk_add_f32 v[168:169], v[178:179], v[180:181]
	v_pk_add_f32 v[170:171], v[182:183], v[184:185]
	s_waitcnt lgkmcnt(2)
	v_add_f32_e32 v149, v149, v159
	s_waitcnt lgkmcnt(1)
	v_add_f32_e32 v159, v160, v166
	s_waitcnt lgkmcnt(0)
; __device__ __forceinline__ unsigned cvt_pk_bf16(float lo, float hi) { unsigned r; asm volatile("v_cvt_pk_bf16_f32 %0, %1, %2" : "=v"(r) : "v"(lo), "v"(hi)); return r; }
; template <int NP> __device__ __forceinline__ void load_rs(const float* ssp, int row0, int fq, float (&rs)[2][4]) {
;     ...
;             for (int m = 0; m < 4; ++m) { float s = (p[ai][m][0] + p[ai][m][1]) + (p[ai][m][2] + p[ai][m][3]); s += __shfl_xor(s, 16); s += __shfl_xor(s, 32); rs[ai][m] = s; }
;     }
; #pragma unroll
;     for (int ai = 0; ai < 2; ++ai)
; #pragma unroll
;         for (int m = 0; m < 4; ++m) rs[ai][m] = __builtin_amdgcn_rsqf(rs[ai][m] * (1.0f / D_MODEL) + RMS_EPS);
;     __device__ __forceinline__ void operator()(const f32x4 (&acc)[2][2][4][2], const Unit& u, int wr, int wc, int fr, int fq) const {
;     ...
;                 const int row = row0 + ai * HALF + m * 16; const float r = rs[ai][m];
;                 const float nrl = r * -1.44269504089f, r2 = r * r;
;                 unsigned pk[4];
; #pragma unroll
;                 for (int q = 0; q < 4; ++q) {
;                     const f32x4 ga = acc[ai][0][m][q >> 1], ua = acc[ai][1][m][q >> 1]; const int e0 = 2 * (q & 1);
;                     const f32x2 g = (f32x2){ga[e0], ga[e0 + 1]}, up = (f32x2){ua[e0], ua[e0 + 1]};
;                     const f32x2 t = g * nrl; f32x2 ex; ex.x = __builtin_amdgcn_exp2f(t.x); ex.y = __builtin_amdgcn_exp2f(t.y);
;                     const f32x2 d = ex + 1.0f; f32x2 rc; rc.x = __builtin_amdgcn_rcpf(d.x); rc.y = __builtin_amdgcn_rcpf(d.y);
;                     const f32x2 o = (g * up) * (rc * r2);
;                     pk[q] = cvt_pk_bf16(o.x, o.y);
;                 }
;                 u32x4 w; w.x = pk[0]; w.y = pk[1]; w.z = pk[2]; w.w = pk[3];
;                 *(u32x4*)(U + (size_t)(row >> 13) * U_SLAB + (size_t)(row & (SEQ - 1)) * U_PITCH + col0) = w;
	v_add_f32_e32 v166, v161, v167
	v_pk_add_f32 v[160:161], v[186:187], v[190:191]
	v_add_f32_e32 v162, v164, v165
	v_add_f32_e32 v164, v168, v169
	v_add_f32_e32 v165, v170, v171
	v_add_f32_e32 v160, v160, v161
	v_mov_b32_e32 v236, v162
	v_mov_b32_e32 v237, v162
	s_nop 1
	v_permlane16_swap_b32_e32 v236, v237
	v_cndmask_b32_e64 v168, v237, v236, s[98:99]
	v_mov_b32_e32 v236, v163
	v_mov_b32_e32 v237, v163
	s_nop 1
	v_permlane16_swap_b32_e32 v236, v237
	v_cndmask_b32_e64 v169, v237, v236, s[98:99]
	v_mov_b32_e32 v236, v164
	v_mov_b32_e32 v237, v164
	s_nop 1
	v_permlane16_swap_b32_e32 v236, v237
	v_cndmask_b32_e64 v170, v237, v236, s[98:99]
	v_mov_b32_e32 v236, v165
	v_mov_b32_e32 v237, v165
	s_nop 1
	v_permlane16_swap_b32_e32 v236, v237
	v_cndmask_b32_e64 v171, v237, v236, s[98:99]
	v_mov_b32_e32 v236, v160
	v_mov_b32_e32 v237, v160
	s_nop 1
	v_permlane16_swap_b32_e32 v236, v237
	v_cndmask_b32_e64 v136, v237, v236, s[98:99]
	s_waitcnt lgkmcnt(4)
	v_add_f32_e32 v162, v162, v168
	s_waitcnt lgkmcnt(3)
	v_add_f32_e32 v163, v163, v169
	s_waitcnt lgkmcnt(2)
	v_add_f32_e32 v161, v164, v170
	s_waitcnt lgkmcnt(1)
	v_add_f32_e32 v165, v165, v171
	s_waitcnt lgkmcnt(0)
	v_add_f32_e32 v136, v160, v136
	v_mov_b32_e32 v236, v162
	v_mov_b32_e32 v237, v162
	s_nop 1
	v_permlane32_swap_b32_e32 v236, v237
	v_cndmask_b32_e64 v168, v237, v236, s[100:101]
	v_mov_b32_e32 v236, v163
	v_mov_b32_e32 v237, v163
	s_nop 1
	v_permlane32_swap_b32_e32 v236, v237
	v_cndmask_b32_e64 v169, v237, v236, s[100:101]
	v_mov_b32_e32 v236, v161
	v_mov_b32_e32 v237, v161
	s_nop 1
	v_permlane32_swap_b32_e32 v236, v237
	v_cndmask_b32_e64 v164, v237, v236, s[100:101]
	v_mov_b32_e32 v236, v165
	v_mov_b32_e32 v237, v165
	s_nop 1
	v_permlane32_swap_b32_e32 v236, v237
	v_cndmask_b32_e64 v167, v237, v236, s[100:101]
	v_mov_b32_e32 v236, v136
	v_mov_b32_e32 v237, v136
	s_nop 1
	v_permlane32_swap_b32_e32 v236, v237
	v_cndmask_b32_e64 v147, v237, v236, s[100:101]
	s_waitcnt lgkmcnt(4)
	v_add_f32_e32 v160, v162, v168
	s_waitcnt lgkmcnt(3)
	v_add_f32_e32 v162, v163, v169
	s_waitcnt lgkmcnt(2)
	v_add_f32_e32 v161, v161, v164
	s_waitcnt lgkmcnt(1)
	v_add_f32_e32 v163, v165, v167
	s_waitcnt lgkmcnt(0)
	v_add_f32_e32 v136, v136, v147
	v_fmamk_f32 v147, v149, 0x3a800000, v157
	v_rsq_f32_e32 v164, v147
	v_fmamk_f32 v147, v159, 0x3a800000, v157
	v_rsq_f32_e32 v165, v147
	v_fmamk_f32 v147, v166, 0x3a800000, v157
	v_rsq_f32_e32 v166, v147
	v_fmamk_f32 v147, v160, 0x3a800000, v157
	v_rsq_f32_e32 v167, v147
	v_fmamk_f32 v147, v162, 0x3a800000, v157
	v_rsq_f32_e32 v168, v147
	v_fmamk_f32 v147, v161, 0x3a800000, v157
	v_rsq_f32_e32 v160, v147
	v_fmamk_f32 v147, v163, 0x3a800000, v157
	v_fmamk_f32 v136, v136, 0x3a800000, v157
	v_rsq_f32_e32 v159, v147
	v_rsq_f32_e32 v147, v136
	v_mul_f32_e32 v136, 0xbfb8aa3b, v164
	v_pk_mul_f32 v[162:163], v[124:125], v[136:137] op_sel_hi:[1,0]
	v_pk_mul_f32 v[124:125], v[126:127], v[136:137] op_sel_hi:[1,0]
	v_exp_f32_e32 v162, v162
	v_exp_f32_e32 v163, v163
	v_exp_f32_e32 v124, v124
	v_exp_f32_e32 v125, v125
	v_mul_f32_e32 v164, v164, v164
	v_pk_add_f32 v[162:163], v[162:163], 1.0 op_sel_hi:[1,0]
	v_bitop3_b32 v161, s2, v158, v150 bitop3:0xc8
	v_rcp_f32_e32 v162, v162
	v_rcp_f32_e32 v163, v163
	v_pk_add_f32 v[124:125], v[124:125], 1.0 op_sel_hi:[1,0]
	s_add_u32 s2, s16, s3
	v_rcp_f32_e32 v124, v124
	v_rcp_f32_e32 v125, v125
	v_pk_mul_f32 v[126:127], v[164:165], v[162:163] op_sel_hi:[0,1]
	v_pk_mul_f32 v[120:121], v[120:121], v[126:127]
	v_pk_mul_f32 v[126:127], v[116:117], v[136:137] op_sel_hi:[1,0]
	v_pk_mul_f32 v[124:125], v[164:165], v[124:125] op_sel_hi:[0,1]
	v_exp_f32_e32 v126, v126
	v_exp_f32_e32 v127, v127
	v_pk_mul_f32 v[122:123], v[122:123], v[124:125]
	v_pk_mul_f32 v[124:125], v[118:119], v[136:137] op_sel_hi:[1,0]
	v_cvt_pk_bf16_f32 v120, v120, v121
	v_cvt_pk_bf16_f32 v121, v122, v123
	v_pk_add_f32 v[122:123], v[126:127], 1.0 op_sel_hi:[1,0]
	v_exp_f32_e32 v124, v124
	v_exp_f32_e32 v125, v125
	v_rcp_f32_e32 v122, v122
	v_rcp_f32_e32 v123, v123
	v_ashrrev_i32_e32 v149, 31, v148
	v_pk_add_f32 v[116:117], v[124:125], 1.0 op_sel_hi:[1,0]
	s_addc_u32 s3, s17, s11
	v_rcp_f32_e32 v116, v116
	v_rcp_f32_e32 v117, v117
	v_pk_mul_f32 v[118:119], v[164:165], v[122:123] op_sel_hi:[0,1]
	v_pk_mul_f32 v[112:113], v[112:113], v[118:119]
	s_nop 0
	v_cvt_pk_bf16_f32 v122, v112, v113
	v_pk_mul_f32 v[112:113], v[164:165], v[116:117] op_sel_hi:[0,1]
	v_mul_f32_e32 v116, 0xbfb8aa3b, v165
	v_pk_mul_f32 v[118:119], v[108:109], v[116:117] op_sel_hi:[1,0]
	v_pk_mul_f32 v[108:109], v[110:111], v[116:117] op_sel_hi:[1,0]
	v_exp_f32_e32 v118, v118
	v_exp_f32_e32 v119, v119
	v_exp_f32_e32 v108, v108
	v_exp_f32_e32 v109, v109
	v_pk_mul_f32 v[112:113], v[114:115], v[112:113]
	v_pk_add_f32 v[118:119], v[118:119], 1.0 op_sel_hi:[1,0]
	v_cvt_pk_bf16_f32 v123, v112, v113
	v_mul_u32_u24_e32 v112, 0xb40, v161
	v_lshlrev_b32_e32 v136, 1, v112
	v_rcp_f32_e32 v118, v118
	v_rcp_f32_e32 v119, v119
	v_lshl_add_u64 v[114:115], s[2:3], 0, v[136:137]
	v_lshlrev_b64 v[112:113], 1, v[148:149]
	v_pk_add_f32 v[108:109], v[108:109], 1.0 op_sel_hi:[1,0]
	v_lshl_add_u64 v[114:115], v[114:115], 0, v[112:113]
	v_rcp_f32_e32 v108, v108
	v_rcp_f32_e32 v109, v109
	global_store_dwordx4 v[114:115], v[120:123], off
	s_nop 1
	v_mul_f32_e32 v120, v165, v165
	v_pk_mul_f32 v[110:111], v[120:121], v[118:119] op_sel_hi:[0,1]
	v_pk_mul_f32 v[104:105], v[104:105], v[110:111]
	v_pk_mul_f32 v[110:111], v[100:101], v[116:117] op_sel_hi:[1,0]
	v_pk_mul_f32 v[108:109], v[120:121], v[108:109] op_sel_hi:[0,1]
	v_exp_f32_e32 v110, v110
	v_exp_f32_e32 v111, v111
	v_pk_mul_f32 v[106:107], v[106:107], v[108:109]
; __device__ __forceinline__ unsigned cvt_pk_bf16(float lo, float hi) { unsigned r; asm volatile("v_cvt_pk_bf16_f32 %0, %1, %2" : "=v"(r) : "v"(lo), "v"(hi)); return r; }
;     __device__ __forceinline__ void operator()(const f32x4 (&acc)[2][2][4][2], const Unit& u, int wr, int wc, int fr, int fq) const {
;     ...
;                 const int row = row0 + ai * HALF + m * 16; const float r = rs[ai][m];
;                 const float nrl = r * -1.44269504089f, r2 = r * r;
;                 unsigned pk[4];
; #pragma unroll
;                 for (int q = 0; q < 4; ++q) {
;                     const f32x4 ga = acc[ai][0][m][q >> 1], ua = acc[ai][1][m][q >> 1]; const int e0 = 2 * (q & 1);
;                     const f32x2 g = (f32x2){ga[e0], ga[e0 + 1]}, up = (f32x2){ua[e0], ua[e0 + 1]};
;                     const f32x2 t = g * nrl; f32x2 ex; ex.x = __builtin_amdgcn_exp2f(t.x); ex.y = __builtin_amdgcn_exp2f(t.y);
;                     const f32x2 d = ex + 1.0f; f32x2 rc; rc.x = __builtin_amdgcn_rcpf(d.x); rc.y = __builtin_amdgcn_rcpf(d.y);
;                     const f32x2 o = (g * up) * (rc * r2);
;                     pk[q] = cvt_pk_bf16(o.x, o.y);
;                 }
;                 u32x4 w; w.x = pk[0]; w.y = pk[1]; w.z = pk[2]; w.w = pk[3];
;                 *(u32x4*)(U + (size_t)(row >> 13) * U_SLAB + (size_t)(row & (SEQ - 1)) * U_PITCH + col0) = w;
	v_pk_mul_f32 v[108:109], v[102:103], v[116:117] op_sel_hi:[1,0]
	v_cvt_pk_bf16_f32 v104, v104, v105
	v_cvt_pk_bf16_f32 v105, v106, v107
	v_pk_add_f32 v[106:107], v[110:111], 1.0 op_sel_hi:[1,0]
	v_exp_f32_e32 v108, v108
	v_exp_f32_e32 v109, v109
	v_rcp_f32_e32 v106, v106
	v_rcp_f32_e32 v107, v107
	v_pk_add_f32 v[100:101], v[108:109], 1.0 op_sel_hi:[1,0]
	s_nop 0
	v_rcp_f32_e32 v100, v100
	v_rcp_f32_e32 v101, v101
	v_pk_mul_f32 v[102:103], v[120:121], v[106:107] op_sel_hi:[0,1]
	v_pk_mul_f32 v[96:97], v[96:97], v[102:103]
	s_nop 0
	v_cvt_pk_bf16_f32 v106, v96, v97
	v_pk_mul_f32 v[96:97], v[120:121], v[100:101] op_sel_hi:[0,1]
	v_pk_mul_f32 v[96:97], v[98:99], v[96:97]
	v_add_co_u32_e32 v100, vcc, s28, v114
	v_cvt_pk_bf16_f32 v107, v96, v97
	v_mul_f32_e32 v96, 0xbfb8aa3b, v166
	v_pk_mul_f32 v[98:99], v[92:93], v[96:97] op_sel_hi:[1,0]
	v_pk_mul_f32 v[92:93], v[94:95], v[96:97] op_sel_hi:[1,0]
	v_exp_f32_e32 v98, v98
	v_exp_f32_e32 v99, v99
	v_exp_f32_e32 v92, v92
	v_exp_f32_e32 v93, v93
	v_addc_co_u32_e32 v101, vcc, 0, v115, vcc
	v_pk_add_f32 v[98:99], v[98:99], 1.0 op_sel_hi:[1,0]
	v_pk_add_f32 v[92:93], v[92:93], 1.0 op_sel_hi:[1,0]
	v_rcp_f32_e32 v98, v98
	v_rcp_f32_e32 v99, v99
	v_rcp_f32_e32 v92, v92
	v_rcp_f32_e32 v93, v93
	global_store_dwordx4 v[100:101], v[104:107], off offset:2048
	v_mul_f32_e32 v100, v166, v166
	v_pk_mul_f32 v[94:95], v[100:101], v[98:99] op_sel_hi:[0,1]
	v_pk_mul_f32 v[88:89], v[88:89], v[94:95]
	v_pk_mul_f32 v[94:95], v[84:85], v[96:97] op_sel_hi:[1,0]
	v_pk_mul_f32 v[92:93], v[100:101], v[92:93] op_sel_hi:[0,1]
	v_exp_f32_e32 v94, v94
	v_exp_f32_e32 v95, v95
	v_pk_mul_f32 v[90:91], v[90:91], v[92:93]
	v_pk_mul_f32 v[92:93], v[86:87], v[96:97] op_sel_hi:[1,0]
	v_cvt_pk_bf16_f32 v88, v88, v89
	v_cvt_pk_bf16_f32 v89, v90, v91
	v_pk_add_f32 v[90:91], v[94:95], 1.0 op_sel_hi:[1,0]
	v_exp_f32_e32 v92, v92
	v_exp_f32_e32 v93, v93
	v_rcp_f32_e32 v90, v90
	v_rcp_f32_e32 v91, v91
	v_pk_add_f32 v[84:85], v[92:93], 1.0 op_sel_hi:[1,0]
	s_nop 0
	v_rcp_f32_e32 v84, v84
	v_rcp_f32_e32 v85, v85
	v_pk_mul_f32 v[86:87], v[100:101], v[90:91] op_sel_hi:[0,1]
	v_pk_mul_f32 v[80:81], v[80:81], v[86:87]
	s_nop 0
	v_cvt_pk_bf16_f32 v90, v80, v81
	v_pk_mul_f32 v[80:81], v[100:101], v[84:85] op_sel_hi:[0,1]
	v_pk_mul_f32 v[80:81], v[82:83], v[80:81]
	v_add_co_u32_e32 v84, vcc, s38, v114
	v_cvt_pk_bf16_f32 v91, v80, v81
	v_mul_f32_e32 v80, 0xbfb8aa3b, v167
	v_pk_mul_f32 v[82:83], v[76:77], v[80:81] op_sel_hi:[1,0]
	v_pk_mul_f32 v[76:77], v[78:79], v[80:81] op_sel_hi:[1,0]
	v_exp_f32_e32 v82, v82
	v_exp_f32_e32 v83, v83
	v_exp_f32_e32 v76, v76
	v_exp_f32_e32 v77, v77
	v_addc_co_u32_e32 v85, vcc, 0, v115, vcc
	v_pk_add_f32 v[82:83], v[82:83], 1.0 op_sel_hi:[1,0]
	v_pk_add_f32 v[76:77], v[76:77], 1.0 op_sel_hi:[1,0]
	v_rcp_f32_e32 v82, v82
	v_rcp_f32_e32 v83, v83
	v_rcp_f32_e32 v76, v76
	v_rcp_f32_e32 v77, v77
	global_store_dwordx4 v[84:85], v[88:91], off
	v_mul_f32_e32 v84, v167, v167
	v_pk_mul_f32 v[78:79], v[84:85], v[82:83] op_sel_hi:[0,1]
	v_pk_mul_f32 v[72:73], v[72:73], v[78:79]
	v_pk_mul_f32 v[78:79], v[68:69], v[80:81] op_sel_hi:[1,0]
	v_pk_mul_f32 v[76:77], v[84:85], v[76:77] op_sel_hi:[0,1]
	v_exp_f32_e32 v78, v78
	v_exp_f32_e32 v79, v79
	v_pk_mul_f32 v[74:75], v[74:75], v[76:77]
	v_pk_mul_f32 v[76:77], v[70:71], v[80:81] op_sel_hi:[1,0]
	v_cvt_pk_bf16_f32 v72, v72, v73
	v_cvt_pk_bf16_f32 v73, v74, v75
	v_pk_add_f32 v[74:75], v[78:79], 1.0 op_sel_hi:[1,0]
	v_exp_f32_e32 v76, v76
	v_exp_f32_e32 v77, v77
	v_rcp_f32_e32 v74, v74
	v_rcp_f32_e32 v75, v75
	v_pk_add_f32 v[68:69], v[76:77], 1.0 op_sel_hi:[1,0]
	s_nop 0
	v_rcp_f32_e32 v68, v68
	v_rcp_f32_e32 v69, v69
	v_pk_mul_f32 v[70:71], v[84:85], v[74:75] op_sel_hi:[0,1]
	v_pk_mul_f32 v[64:65], v[64:65], v[70:71]
	s_nop 0
	v_cvt_pk_bf16_f32 v74, v64, v65
	v_pk_mul_f32 v[64:65], v[84:85], v[68:69] op_sel_hi:[0,1]
	v_pk_mul_f32 v[64:65], v[66:67], v[64:65]
	v_and_b32_e32 v69, 0x1fcf, v146
	v_cvt_pk_bf16_f32 v75, v64, v65
	v_add_co_u32_e32 v64, vcc, s39, v114
	v_mul_f32_e32 v68, v168, v168
	s_nop 0
	v_addc_co_u32_e32 v65, vcc, 0, v115, vcc
	global_store_dwordx4 v[64:65], v[72:75], off offset:2048
	v_mul_f32_e32 v64, 0xbfb8aa3b, v168
	v_pk_mul_f32 v[66:67], v[60:61], v[64:65] op_sel_hi:[1,0]
	v_ashrrev_i32_e32 v65, 13, v146
	v_exp_f32_e32 v66, v66
	v_exp_f32_e32 v67, v67
	v_pk_mul_f32 v[60:61], v[62:63], v[64:65] op_sel_hi:[1,0]
	v_pk_add_f32 v[66:67], v[66:67], 1.0 op_sel_hi:[1,0]
	v_exp_f32_e32 v60, v60
	v_exp_f32_e32 v61, v61
	v_rcp_f32_e32 v66, v66
	v_rcp_f32_e32 v67, v67
	v_pk_add_f32 v[60:61], v[60:61], 1.0 op_sel_hi:[1,0]
	s_nop 0
	v_rcp_f32_e32 v60, v60
	v_rcp_f32_e32 v61, v61
	v_pk_mul_f32 v[62:63], v[68:69], v[66:67] op_sel_hi:[0,1]
	v_pk_mul_f32 v[56:57], v[56:57], v[62:63]
	v_pk_mul_f32 v[62:63], v[52:53], v[64:65] op_sel_hi:[1,0]
	v_pk_mul_f32 v[60:61], v[68:69], v[60:61] op_sel_hi:[0,1]
	v_exp_f32_e32 v62, v62
	v_exp_f32_e32 v63, v63
	v_pk_mul_f32 v[58:59], v[58:59], v[60:61]
	v_pk_mul_f32 v[60:61], v[54:55], v[64:65] op_sel_hi:[1,0]
	v_cvt_pk_bf16_f32 v56, v56, v57
	v_cvt_pk_bf16_f32 v57, v58, v59
	v_pk_add_f32 v[58:59], v[62:63], 1.0 op_sel_hi:[1,0]
	v_exp_f32_e32 v60, v60
	v_exp_f32_e32 v61, v61
	v_rcp_f32_e32 v58, v58
	v_rcp_f32_e32 v59, v59
	v_pk_add_f32 v[52:53], v[60:61], 1.0 op_sel_hi:[1,0]
	s_nop 0
	v_rcp_f32_e32 v52, v52
	v_rcp_f32_e32 v53, v53
	v_pk_mul_f32 v[54:55], v[68:69], v[58:59] op_sel_hi:[0,1]
	v_pk_mul_f32 v[48:49], v[48:49], v[54:55]
; __device__ __forceinline__ unsigned cvt_pk_bf16(float lo, float hi) { unsigned r; asm volatile("v_cvt_pk_bf16_f32 %0, %1, %2" : "=v"(r) : "v"(lo), "v"(hi)); return r; }
; #define PG8_BAR __builtin_amdgcn_s_barrier()
;     __device__ __forceinline__ void operator()(const f32x4 (&acc)[2][2][4][2], const Unit& u, int wr, int wc, int fr, int fq) const {
;     ...
;                 const int row = row0 + ai * HALF + m * 16; const float r = rs[ai][m];
;                 const float nrl = r * -1.44269504089f, r2 = r * r;
;                 unsigned pk[4];
; #pragma unroll
;                 for (int q = 0; q < 4; ++q) {
;                     const f32x4 ga = acc[ai][0][m][q >> 1], ua = acc[ai][1][m][q >> 1]; const int e0 = 2 * (q & 1);
;                     const f32x2 g = (f32x2){ga[e0], ga[e0 + 1]}, up = (f32x2){ua[e0], ua[e0 + 1]};
;                     const f32x2 t = g * nrl; f32x2 ex; ex.x = __builtin_amdgcn_exp2f(t.x); ex.y = __builtin_amdgcn_exp2f(t.y);
;                     const f32x2 d = ex + 1.0f; f32x2 rc; rc.x = __builtin_amdgcn_rcpf(d.x); rc.y = __builtin_amdgcn_rcpf(d.y);
;                     const f32x2 o = (g * up) * (rc * r2);
;                     pk[q] = cvt_pk_bf16(o.x, o.y);
;                 }
;                 u32x4 w; w.x = pk[0]; w.y = pk[1]; w.z = pk[2]; w.w = pk[3];
;                 *(u32x4*)(U + (size_t)(row >> 13) * U_SLAB + (size_t)(row & (SEQ - 1)) * U_PITCH + col0) = w;
; template <class Epi>
; __device__ __forceinline__ void gemm_phase(LAS unsigned char* lds, const Gemm g, const StaticOrder& S, const Epi& E) {
;     ...
;         if (!has_next) break;
; #pragma unroll
;         for (int a = 0; a < 2; ++a)
; #pragma unroll
;             for (int b = 0; b < 2; ++b)
; #pragma unroll
;                 for (int m = 0; m < 4; ++m)
; #pragma unroll
;                     for (int n = 0; n < 2; ++n) acc[a][b][m][n] = (f32x4){0.f, 0.f, 0.f, 0.f};
;         cur = nxt; cA = nA; cB = nB; ++ui;
;         if (wr == 1) PG8_BAR;
	v_mul_f32_e32 v54, v160, v160
	v_cvt_pk_bf16_f32 v58, v48, v49
	v_pk_mul_f32 v[48:49], v[68:69], v[52:53] op_sel_hi:[0,1]
	v_pk_mul_f32 v[48:49], v[50:51], v[48:49]
	v_mul_u32_u24_e32 v50, 0xb40, v69
	v_lshlrev_b32_e32 v136, 1, v50
	v_mul_f32_e32 v50, 0xbfb8aa3b, v160
	v_pk_mul_f32 v[52:53], v[44:45], v[50:51] op_sel_hi:[1,0]
	v_pk_mul_f32 v[44:45], v[46:47], v[50:51] op_sel_hi:[1,0]
	v_exp_f32_e32 v52, v52
	v_exp_f32_e32 v53, v53
	v_exp_f32_e32 v44, v44
	v_exp_f32_e32 v45, v45
	v_cvt_pk_bf16_f32 v59, v48, v49
	v_pk_add_f32 v[52:53], v[52:53], 1.0 op_sel_hi:[1,0]
	v_mov_b64_e32 v[48:49], s[16:17]
	v_rcp_f32_e32 v52, v52
	v_rcp_f32_e32 v53, v53
	v_pk_add_f32 v[44:45], v[44:45], 1.0 op_sel_hi:[1,0]
	v_mad_i64_i32 v[48:49], s[2:3], v65, s37, v[48:49]
	v_rcp_f32_e32 v44, v44
	v_rcp_f32_e32 v45, v45
	v_pk_mul_f32 v[46:47], v[54:55], v[52:53] op_sel_hi:[0,1]
	v_pk_mul_f32 v[40:41], v[40:41], v[46:47]
	v_pk_mul_f32 v[46:47], v[36:37], v[50:51] op_sel_hi:[1,0]
	v_pk_mul_f32 v[44:45], v[54:55], v[44:45] op_sel_hi:[0,1]
	v_exp_f32_e32 v46, v46
	v_exp_f32_e32 v47, v47
	v_pk_mul_f32 v[42:43], v[42:43], v[44:45]
	v_pk_mul_f32 v[44:45], v[38:39], v[50:51] op_sel_hi:[1,0]
	v_lshl_add_u64 v[48:49], v[48:49], 0, v[136:137]
	v_exp_f32_e32 v44, v44
	v_exp_f32_e32 v45, v45
	v_lshl_add_u64 v[48:49], v[48:49], 0, v[112:113]
	global_store_dwordx4 v[48:49], v[56:59], off
	v_cvt_pk_bf16_f32 v40, v40, v41
	v_cvt_pk_bf16_f32 v41, v42, v43
	v_pk_add_f32 v[42:43], v[46:47], 1.0 op_sel_hi:[1,0]
	v_pk_add_f32 v[36:37], v[44:45], 1.0 op_sel_hi:[1,0]
	v_rcp_f32_e32 v42, v42
	v_rcp_f32_e32 v43, v43
	v_rcp_f32_e32 v36, v36
	v_rcp_f32_e32 v37, v37
	s_mov_b64 s[2:3], -1
	v_pk_mul_f32 v[38:39], v[54:55], v[42:43] op_sel_hi:[0,1]
	v_pk_mul_f32 v[32:33], v[32:33], v[38:39]
	s_nop 0
	v_cvt_pk_bf16_f32 v42, v32, v33
	v_pk_mul_f32 v[32:33], v[54:55], v[36:37] op_sel_hi:[0,1]
	v_pk_mul_f32 v[32:33], v[34:35], v[32:33]
	v_add_co_u32_e32 v36, vcc, s28, v48
	v_cvt_pk_bf16_f32 v43, v32, v33
	v_mul_f32_e32 v32, 0xbfb8aa3b, v159
	v_pk_mul_f32 v[34:35], v[28:29], v[32:33] op_sel_hi:[1,0]
	v_pk_mul_f32 v[28:29], v[30:31], v[32:33] op_sel_hi:[1,0]
	v_exp_f32_e32 v34, v34
	v_exp_f32_e32 v35, v35
	v_exp_f32_e32 v28, v28
	v_exp_f32_e32 v29, v29
	v_addc_co_u32_e32 v37, vcc, 0, v49, vcc
	v_pk_add_f32 v[34:35], v[34:35], 1.0 op_sel_hi:[1,0]
	v_pk_add_f32 v[28:29], v[28:29], 1.0 op_sel_hi:[1,0]
	v_rcp_f32_e32 v34, v34
	v_rcp_f32_e32 v35, v35
	v_rcp_f32_e32 v28, v28
	v_rcp_f32_e32 v29, v29
	global_store_dwordx4 v[36:37], v[40:43], off offset:2048
	v_mul_f32_e32 v36, v159, v159
	v_pk_mul_f32 v[30:31], v[36:37], v[34:35] op_sel_hi:[0,1]
	v_pk_mul_f32 v[24:25], v[24:25], v[30:31]
	v_pk_mul_f32 v[30:31], v[20:21], v[32:33] op_sel_hi:[1,0]
	v_pk_mul_f32 v[28:29], v[36:37], v[28:29] op_sel_hi:[0,1]
	v_exp_f32_e32 v30, v30
	v_exp_f32_e32 v31, v31
	v_pk_mul_f32 v[26:27], v[26:27], v[28:29]
	v_pk_mul_f32 v[28:29], v[22:23], v[32:33] op_sel_hi:[1,0]
	v_cvt_pk_bf16_f32 v24, v24, v25
	v_cvt_pk_bf16_f32 v25, v26, v27
	v_pk_add_f32 v[26:27], v[30:31], 1.0 op_sel_hi:[1,0]
	v_exp_f32_e32 v28, v28
	v_exp_f32_e32 v29, v29
	v_rcp_f32_e32 v26, v26
	v_rcp_f32_e32 v27, v27
	v_pk_add_f32 v[20:21], v[28:29], 1.0 op_sel_hi:[1,0]
	s_nop 0
	v_rcp_f32_e32 v20, v20
	v_rcp_f32_e32 v21, v21
	v_pk_mul_f32 v[22:23], v[36:37], v[26:27] op_sel_hi:[0,1]
	v_pk_mul_f32 v[16:17], v[16:17], v[22:23]
	s_nop 0
	v_cvt_pk_bf16_f32 v26, v16, v17
	v_pk_mul_f32 v[16:17], v[36:37], v[20:21] op_sel_hi:[0,1]
	v_pk_mul_f32 v[16:17], v[18:19], v[16:17]
	v_add_co_u32_e32 v20, vcc, s38, v48
	v_cvt_pk_bf16_f32 v27, v16, v17
	v_mul_f32_e32 v16, 0xbfb8aa3b, v147
	v_pk_mul_f32 v[18:19], v[12:13], v[16:17] op_sel_hi:[1,0]
	v_pk_mul_f32 v[12:13], v[14:15], v[16:17] op_sel_hi:[1,0]
	v_exp_f32_e32 v18, v18
	v_exp_f32_e32 v19, v19
	v_exp_f32_e32 v12, v12
	v_exp_f32_e32 v13, v13
	v_addc_co_u32_e32 v21, vcc, 0, v49, vcc
	v_pk_add_f32 v[18:19], v[18:19], 1.0 op_sel_hi:[1,0]
	v_pk_add_f32 v[12:13], v[12:13], 1.0 op_sel_hi:[1,0]
	v_rcp_f32_e32 v18, v18
	v_rcp_f32_e32 v19, v19
	v_rcp_f32_e32 v12, v12
	v_rcp_f32_e32 v13, v13
	global_store_dwordx4 v[20:21], v[24:27], off
	v_mul_f32_e32 v20, v147, v147
	v_pk_mul_f32 v[14:15], v[20:21], v[18:19] op_sel_hi:[0,1]
	v_pk_mul_f32 v[8:9], v[8:9], v[14:15]
	v_pk_mul_f32 v[14:15], v[4:5], v[16:17] op_sel_hi:[1,0]
	v_pk_mul_f32 v[12:13], v[20:21], v[12:13] op_sel_hi:[0,1]
	v_exp_f32_e32 v14, v14
	v_exp_f32_e32 v15, v15
	v_pk_mul_f32 v[10:11], v[10:11], v[12:13]
	v_pk_mul_f32 v[12:13], v[6:7], v[16:17] op_sel_hi:[1,0]
	v_cvt_pk_bf16_f32 v8, v8, v9
	v_cvt_pk_bf16_f32 v9, v10, v11
	v_pk_add_f32 v[10:11], v[14:15], 1.0 op_sel_hi:[1,0]
	v_exp_f32_e32 v12, v12
	v_exp_f32_e32 v13, v13
	v_rcp_f32_e32 v10, v10
	v_rcp_f32_e32 v11, v11
	v_pk_add_f32 v[4:5], v[12:13], 1.0 op_sel_hi:[1,0]
	s_nop 0
	v_rcp_f32_e32 v4, v4
	v_rcp_f32_e32 v5, v5
	v_pk_mul_f32 v[6:7], v[20:21], v[10:11] op_sel_hi:[0,1]
	v_pk_mul_f32 v[0:1], v[0:1], v[6:7]
	s_nop 0
	v_cvt_pk_bf16_f32 v10, v0, v1
	v_pk_mul_f32 v[0:1], v[20:21], v[4:5] op_sel_hi:[0,1]
	v_pk_mul_f32 v[0:1], v[2:3], v[0:1]
	s_nop 0
	v_cvt_pk_bf16_f32 v11, v0, v1
	v_add_co_u32_e32 v0, vcc, 0x43000, v48
	s_nop 1
	v_addc_co_u32_e32 v1, vcc, 0, v49, vcc
	s_andn2_b64 vcc, exec, s[4:5]
	global_store_dwordx4 v[0:1], v[8:11], off offset:2048
	s_cbranch_vccnz .LBB0_925
	s_andn2_b64 vcc, exec, s[0:1]
	s_cbranch_vccnz .LBB0_924
	s_barrier
	s_branch .LBB0_924

; #define LAS __attribute__((address_space(3)))
; __global__ void __launch_bounds__(512, 2) mk_fwd(Args a) {
;     extern __shared__ __attribute__((aligned(16))) unsigned char lds_raw[];
;     LAS unsigned char* lds = (LAS unsigned char*)lds_raw;
;     cg::grid_group grid = cg::this_grid();
;     const int tid = threadIdx.x, lane = tid & 63, wave = __builtin_amdgcn_readfirstlane(tid >> 6);
;     const int G = gridDim.x, bx = blockIdx.x;
	.amdhsa_kernel _Z6mk_fwd4Args
		.amdhsa_group_segment_fixed_size 16384
		.amdhsa_private_segment_fixed_size 0
		.amdhsa_kernarg_size 408
		.amdhsa_user_sgpr_count 2
		.amdhsa_user_sgpr_dispatch_ptr 0
		.amdhsa_user_sgpr_queue_ptr 0
		.amdhsa_user_sgpr_kernarg_segment_ptr 1
		.amdhsa_user_sgpr_dispatch_id 0
		.amdhsa_user_sgpr_kernarg_preload_length 0
		.amdhsa_user_sgpr_kernarg_preload_offset 0
		.amdhsa_user_sgpr_private_segment_size 0
		.amdhsa_uses_dynamic_stack 0
		.amdhsa_enable_private_segment 0
		.amdhsa_system_sgpr_workgroup_id_x 1
		.amdhsa_system_sgpr_workgroup_id_y 0
		.amdhsa_system_sgpr_workgroup_id_z 0
		.amdhsa_system_sgpr_workgroup_info 0
		.amdhsa_system_vgpr_workitem_id 2
		.amdhsa_next_free_vgpr 240
		.amdhsa_next_free_sgpr 102
		.amdhsa_accum_offset 240
		.amdhsa_reserve_vcc 1
		.amdhsa_float_round_mode_32 0
		.amdhsa_float_round_mode_16_64 0
		.amdhsa_float_denorm_mode_32 3
		.amdhsa_float_denorm_mode_16_64 3
		.amdhsa_dx10_clamp 1
		.amdhsa_ieee_mode 1
		.amdhsa_fp16_overflow 0
		.amdhsa_tg_split 0
		.amdhsa_exception_fp_ieee_invalid_op 0
		.amdhsa_exception_fp_denorm_src 0
		.amdhsa_exception_fp_ieee_div_zero 0
		.amdhsa_exception_fp_ieee_overflow 0
		.amdhsa_exception_fp_ieee_underflow 0
		.amdhsa_exception_fp_ieee_inexact 0
		.amdhsa_exception_int_div_zero 0
	.end_amdhsa_kernel

; #define LAS __attribute__((address_space(3)))
; __global__ void __launch_bounds__(512, 2) mk_fwd(Args a) {
;     extern __shared__ __attribute__((aligned(16))) unsigned char lds_raw[];
;     LAS unsigned char* lds = (LAS unsigned char*)lds_raw;
;     cg::grid_group grid = cg::this_grid();
;     const int tid = threadIdx.x, lane = tid & 63, wave = __builtin_amdgcn_readfirstlane(tid >> 6);
;     const int G = gridDim.x, bx = blockIdx.x;
amdhsa.kernels:
  - .agpr_count:     0
    .args:
      - .offset:         0
        .size:           152
        .value_kind:     by_value
      - .offset:         152
        .size:           4
        .value_kind:     hidden_block_count_x
      - .offset:         156
        .size:           4
        .value_kind:     hidden_block_count_y
      - .offset:         160
        .size:           4
        .value_kind:     hidden_block_count_z
      - .offset:         164
        .size:           2
        .value_kind:     hidden_group_size_x
      - .offset:         166
        .size:           2
        .value_kind:     hidden_group_size_y
      - .offset:         168
        .size:           2
        .value_kind:     hidden_group_size_z
      - .offset:         170
        .size:           2
        .value_kind:     hidden_remainder_x
      - .offset:         172
        .size:           2
        .value_kind:     hidden_remainder_y
      - .offset:         174
        .size:           2
        .value_kind:     hidden_remainder_z
      - .offset:         192
        .size:           8
        .value_kind:     hidden_global_offset_x
      - .offset:         200
        .size:           8
        .value_kind:     hidden_global_offset_y
      - .offset:         208
        .size:           8
        .value_kind:     hidden_global_offset_z
      - .offset:         216
        .size:           2
        .value_kind:     hidden_grid_dims
      - .offset:         240
        .size:           8
        .value_kind:     hidden_multigrid_sync_arg
      - .offset:         272
        .size:           4
        .value_kind:     hidden_dynamic_lds_size
    .group_segment_fixed_size: 16384
    .kernarg_segment_align: 8
    .kernarg_segment_size: 408
    .language:       OpenCL C
    .language_version:
      - 2
      - 0
    .max_flat_workgroup_size: 512
    .name:           _Z6mk_fwd4Args
    .private_segment_fixed_size: 0
    .sgpr_count:     108
    .sgpr_spill_count: 94
    .symbol:         _Z6mk_fwd4Args.kd
    .uniform_work_group_size: 1
    .uses_dynamic_stack: false
    .vgpr_count:     240
    .vgpr_spill_count: 0
    .wavefront_size: 64
